# layer-0 L1 invalidate moved from the in-proj->MIX1 group barrier to the MIX1->scan full barrier (MIX1 reads nothing this CU loaded before); also dropped before the final phase
# speedup vs baseline: 1.0108x; 1.0034x over previous
.Lmy_xbG_known:
	s_cmp_eq_u32 s18, 2
	s_cbranch_scc0 .Lmy_xbA
	s_and_b32 s3, s2, 7
	s_lshl_b32 s3, s3, 8
	s_add_u32 s16, s74, s3
	s_addc_u32 s17, s75, 0
	s_add_u32 s16, s16, 0x2400
	s_addc_u32 s17, s17, 0
	v_readlane_b32 s18, v255, 23
	s_add_i32 s18, s18, 1
	s_nop 3
	v_writelane_b32 v255, s18, 23
	s_lshl_b32 s18, s18, 5
	v_mov_b32_e32 v4, s18
	global_atomic_add v163, v212, s[16:17]
	s_sub_i32 s3, s68, 1
	s_lshl_b32 s3, 1, s3
	s_and_b32 s3, s3, 0x18b2
	s_cmp_lg_u32 s3, 0
	s_cbranch_scc1 .Lmy_xbG_noinv
	buffer_inv sc1

.Lmy_xb_poll:
	s_mov_b64 exec, s[14:15]
	s_mov_b32 s3, 0
	s_sub_i32 s18, s68, 1
	s_lshl_b32 s18, 1, s18
	s_and_b32 s18, s18, 0x4609
	s_cmp_lg_u32 s18, 0
	s_cbranch_scc1 .Lmy_xb_noinv2
	buffer_inv sc1
